# transposer loads staggered in time per loader wave (s_sleep 4/9/14/19) so they do not coincide with the operand DMA burst after each barrier
# baseline (speedup 1.0000x reference)
; #define LAS __attribute__((address_space(3)))
; #define GAS __attribute__((address_space(1)))
; __device__ __forceinline__ void p0_transpose_item(const GAS float* W, int K, int N, GAS bf16* WT, int mode, LAS float* scr, int item, int lane) {
;     const int nblk = N / 32, kb = item / nblk, nb = item % nblk, k0 = 64 * kb, n0 = 32 * nb;
;     int r0 = n0;
;     if (mode & 1) { r0 = (n0 < DFF) ? (n0 / 128) * 256 + (n0 % 128) : ((n0 - DFF) / 128) * 256 + 128 + ((n0 - DFF) % 128); }
;     float tv[32];
; #pragma unroll
;     for (int i = 0; i < 32; ++i) tv[i] = __builtin_nontemporal_load(&W[(size_t)(k0 + 2 * i + (lane >> 5)) * N + n0 + (lane & 31)]);
.Lxp_go0:
	s_sleep 4
	s_cmp_eq_u32 s1, 0
	s_cbranch_scc1 .Lxp_sl0
	s_sleep 5
	s_cmp_eq_u32 s1, 1
	s_cbranch_scc1 .Lxp_sl0
	s_sleep 5
	s_cmp_eq_u32 s1, 2
	s_cbranch_scc1 .Lxp_sl0
	s_sleep 5
